# rtab rsqrt tables: loads batched for UP and w_in phases
# baseline (speedup 1.0000x reference)
.LBB0_298:
	s_lshl_b64 s[6:7], s[2:3], 18
	v_readlane_b32 s18, v250, 23
	v_readlane_b32 s19, v250, 24
	s_add_u32 s6, s18, s6
	s_addc_u32 s7, s19, s7
	s_and_saveexec_b64 s[22:23], s[0:1]
	s_cbranch_execz .LBB0_300
	s_ashr_i32 s8, s8, 3
	s_add_i32 s8, s9, s8
	s_ashr_i32 s9, s8, 31
	s_lshr_b32 s9, s9, 24
	s_add_i32 s9, s8, s9
	s_and_b32 s18, s9, 0xff00
	s_sub_i32 s8, s8, s18
	s_sext_i32_i16 s18, s8
	s_bfe_u32 s18, s18, 0x3001c
	s_add_i32 s18, s8, s18
	s_and_b32 s18, s18, 0xfff8
	s_sub_i32 s8, s8, s18
	s_sext_i32_i16 s8, s8
	s_lshl_b32 s9, s9, 3
	s_and_b32 s9, s9, 0xfffff800
	s_lshl_b32 s8, s8, 8
	s_add_i32 s8, s8, s9
	v_add_u32_e32 v2, s8, v208
	v_ashrrev_i32_e32 v3, 31, v2
	v_lshl_add_u64 v[2:3], v[2:3], 4, s[6:7]
	global_load_dwordx4 v[44:47], v[2:3], off

.LBB0_304:
	s_ashr_i32 s8, s8, 3
	s_add_i32 s8, s9, s8
	s_ashr_i32 s9, s8, 31
	s_lshr_b32 s9, s9, 24
	s_add_i32 s9, s8, s9
	s_ashr_i32 s18, s9, 8
	s_lshl_b32 s18, s18, 3
	s_sub_i32 s19, 64, s18
	s_min_i32 s19, s19, 8
	s_abs_i32 s19, s19
	v_cvt_f32_u32_e32 v0, s19
	s_sub_i32 s28, 0, s19
	s_and_b32 s9, s9, 0xffffff00
	s_sub_i32 s8, s8, s9
	v_rcp_iflag_f32_e32 v0, v0
	s_ashr_i32 s9, s8, 31
	s_abs_i32 s8, s8
	v_mul_f32_e32 v0, 0x4f7ffffe, v0
	v_cvt_u32_f32_e32 v0, v0
	s_nop 0
	v_readfirstlane_b32 s29, v0
	s_mul_i32 s28, s28, s29
	s_mul_hi_u32 s28, s29, s28
	s_add_i32 s29, s29, s28
	s_mul_hi_u32 s28, s8, s29
	s_mul_i32 s28, s28, s19
	s_sub_i32 s8, s8, s28
	s_sub_i32 s28, s8, s19
	s_cmp_ge_u32 s8, s19
	s_cselect_b32 s8, s28, s8
	s_sub_i32 s28, s8, s19
	s_cmp_ge_u32 s8, s19
	s_cselect_b32 s8, s28, s8
	s_xor_b32 s8, s8, s9
	s_sub_i32 s8, s8, s9
	s_add_i32 s8, s8, s18
	v_lshl_add_u32 v2, s8, 8, v208
	v_ashrrev_i32_e32 v3, 31, v2
	v_lshl_add_u64 v[2:3], v[2:3], 4, s[6:7]
	global_load_dwordx4 v[48:51], v[2:3], off
	v_readlane_b32 s29, v250, 29

.LBB0_309:
	s_ashr_i32 s8, s8, 3
	s_add_i32 s8, s9, s8
	s_ashr_i32 s9, s8, 31
	s_lshr_b32 s9, s9, 24
	s_add_i32 s9, s8, s9
	s_ashr_i32 s18, s9, 8
	s_lshl_b32 s18, s18, 3
	s_sub_i32 s19, 64, s18
	s_min_i32 s19, s19, 8
	s_abs_i32 s19, s19
	v_cvt_f32_u32_e32 v0, s19
	s_sub_i32 s28, 0, s19
	s_and_b32 s9, s9, 0xffffff00
	s_sub_i32 s8, s8, s9
	v_rcp_iflag_f32_e32 v0, v0
	s_ashr_i32 s9, s8, 31
	s_abs_i32 s8, s8
	v_mul_f32_e32 v0, 0x4f7ffffe, v0
	v_cvt_u32_f32_e32 v0, v0
	s_nop 0
	v_readfirstlane_b32 s29, v0
	s_mul_i32 s28, s28, s29
	s_mul_hi_u32 s28, s29, s28
	s_add_i32 s29, s29, s28
	s_mul_hi_u32 s28, s8, s29
	s_mul_i32 s28, s28, s19
	s_sub_i32 s8, s8, s28
	s_sub_i32 s28, s8, s19
	s_cmp_ge_u32 s8, s19
	s_cselect_b32 s8, s28, s8
	s_sub_i32 s28, s8, s19
	s_cmp_ge_u32 s8, s19
	s_cselect_b32 s8, s28, s8
	s_xor_b32 s8, s8, s9
	s_sub_i32 s8, s8, s9
	s_add_i32 s8, s8, s18
	v_lshl_add_u32 v2, s8, 8, v208
	v_ashrrev_i32_e32 v3, 31, v2
	v_lshl_add_u64 v[2:3], v[2:3], 4, s[6:7]
	global_load_dwordx4 v[52:55], v[2:3], off
	v_readlane_b32 s29, v250, 29

.LBB0_314:
	s_ashr_i32 s8, s8, 3
	s_add_i32 s8, s9, s8
	s_ashr_i32 s9, s8, 31
	s_lshr_b32 s9, s9, 24
	s_add_i32 s9, s8, s9
	s_ashr_i32 s18, s9, 8
	s_lshl_b32 s18, s18, 3
	s_sub_i32 s19, 64, s18
	s_min_i32 s19, s19, 8
	s_abs_i32 s19, s19
	v_cvt_f32_u32_e32 v0, s19
	s_sub_i32 s28, 0, s19
	s_and_b32 s9, s9, 0xffffff00
	s_sub_i32 s8, s8, s9
	v_rcp_iflag_f32_e32 v0, v0
	s_ashr_i32 s9, s8, 31
	s_abs_i32 s8, s8
	v_mul_f32_e32 v0, 0x4f7ffffe, v0
	v_cvt_u32_f32_e32 v0, v0
	s_nop 0
	v_readfirstlane_b32 s29, v0
	s_mul_i32 s28, s28, s29
	s_mul_hi_u32 s28, s29, s28
	s_add_i32 s29, s29, s28
	s_mul_hi_u32 s28, s8, s29
	s_mul_i32 s28, s28, s19
	s_sub_i32 s8, s8, s28
	s_sub_i32 s28, s8, s19
	s_cmp_ge_u32 s8, s19
	s_cselect_b32 s8, s28, s8
	s_sub_i32 s28, s8, s19
	s_cmp_ge_u32 s8, s19
	s_cselect_b32 s8, s28, s8
	s_xor_b32 s8, s8, s9
	s_sub_i32 s8, s8, s9
	s_add_i32 s8, s8, s18
	v_lshl_add_u32 v2, s8, 8, v208
	v_ashrrev_i32_e32 v3, 31, v2
	v_lshl_add_u64 v[2:3], v[2:3], 4, s[6:7]
	global_load_dwordx4 v[56:59], v[2:3], off
	v_readlane_b32 s29, v250, 29

.LBB0_319:
	s_ashr_i32 s8, s8, 3
	s_add_i32 s8, s9, s8
	s_ashr_i32 s9, s8, 31
	s_lshr_b32 s9, s9, 24
	s_add_i32 s9, s8, s9
	s_ashr_i32 s18, s9, 8
	s_lshl_b32 s18, s18, 3
	s_sub_i32 s19, 64, s18
	s_min_i32 s19, s19, 8
	s_abs_i32 s19, s19
	v_cvt_f32_u32_e32 v0, s19
	s_sub_i32 s28, 0, s19
	s_and_b32 s9, s9, 0xffffff00
	s_sub_i32 s8, s8, s9
	v_rcp_iflag_f32_e32 v0, v0
	s_ashr_i32 s9, s8, 31
	s_abs_i32 s8, s8
	v_mul_f32_e32 v0, 0x4f7ffffe, v0
	v_cvt_u32_f32_e32 v0, v0
	s_nop 0
	v_readfirstlane_b32 s29, v0
	s_mul_i32 s28, s28, s29
	s_mul_hi_u32 s28, s29, s28
	s_add_i32 s29, s29, s28
	s_mul_hi_u32 s28, s8, s29
	s_mul_i32 s28, s28, s19
	s_sub_i32 s8, s8, s28
	s_sub_i32 s28, s8, s19
	s_cmp_ge_u32 s8, s19
	s_cselect_b32 s8, s28, s8
	s_sub_i32 s28, s8, s19
	s_cmp_ge_u32 s8, s19
	s_cselect_b32 s8, s28, s8
	s_xor_b32 s8, s8, s9
	s_sub_i32 s8, s8, s9
	s_add_i32 s8, s8, s18
	v_lshl_add_u32 v2, s8, 8, v208
	v_ashrrev_i32_e32 v3, 31, v2
	v_lshl_add_u64 v[2:3], v[2:3], 4, s[6:7]
	global_load_dwordx4 v[60:63], v[2:3], off
	v_readlane_b32 s29, v250, 29

.LBB0_324:
	s_ashr_i32 s8, s8, 3
	s_add_i32 s8, s9, s8
	s_ashr_i32 s9, s8, 31
	s_lshr_b32 s9, s9, 24
	s_add_i32 s9, s8, s9
	s_ashr_i32 s18, s9, 8
	s_lshl_b32 s18, s18, 3
	s_sub_i32 s19, 64, s18
	s_min_i32 s19, s19, 8
	s_abs_i32 s19, s19
	v_cvt_f32_u32_e32 v0, s19
	s_sub_i32 s28, 0, s19
	s_and_b32 s9, s9, 0xffffff00
	s_sub_i32 s8, s8, s9
	v_rcp_iflag_f32_e32 v0, v0
	s_ashr_i32 s9, s8, 31
	s_abs_i32 s8, s8
	v_mul_f32_e32 v0, 0x4f7ffffe, v0
	v_cvt_u32_f32_e32 v0, v0
	s_nop 0
	v_readfirstlane_b32 s29, v0
	s_mul_i32 s28, s28, s29
	s_mul_hi_u32 s28, s29, s28
	s_add_i32 s29, s29, s28
	s_mul_hi_u32 s28, s8, s29
	s_mul_i32 s28, s28, s19
	s_sub_i32 s8, s8, s28
	s_sub_i32 s28, s8, s19
	s_cmp_ge_u32 s8, s19
	s_cselect_b32 s8, s28, s8
	s_sub_i32 s28, s8, s19
	s_cmp_ge_u32 s8, s19
	s_cselect_b32 s8, s28, s8
	s_xor_b32 s8, s8, s9
	s_sub_i32 s8, s8, s9
	s_add_i32 s8, s8, s18
	v_lshl_add_u32 v2, s8, 8, v208
	v_ashrrev_i32_e32 v3, 31, v2
	v_lshl_add_u64 v[2:3], v[2:3], 4, s[6:7]
	global_load_dwordx4 v[64:67], v[2:3], off
	v_readlane_b32 s29, v250, 29

.LBB0_329:
	s_ashr_i32 s8, s8, 3
	s_add_i32 s8, s9, s8
	s_ashr_i32 s9, s8, 31
	s_lshr_b32 s9, s9, 24
	s_add_i32 s9, s8, s9
	s_ashr_i32 s18, s9, 8
	s_lshl_b32 s18, s18, 3
	s_sub_i32 s19, 64, s18
	s_min_i32 s19, s19, 8
	s_abs_i32 s19, s19
	v_cvt_f32_u32_e32 v0, s19
	s_sub_i32 s28, 0, s19
	s_and_b32 s9, s9, 0xffffff00
	s_sub_i32 s8, s8, s9
	v_rcp_iflag_f32_e32 v0, v0
	s_ashr_i32 s9, s8, 31
	s_abs_i32 s8, s8
	v_mul_f32_e32 v0, 0x4f7ffffe, v0
	v_cvt_u32_f32_e32 v0, v0
	s_nop 0
	v_readfirstlane_b32 s29, v0
	s_mul_i32 s28, s28, s29
	s_mul_hi_u32 s28, s29, s28
	s_add_i32 s29, s29, s28
	s_mul_hi_u32 s28, s8, s29
	s_mul_i32 s28, s28, s19
	s_sub_i32 s8, s8, s28
	s_sub_i32 s28, s8, s19
	s_cmp_ge_u32 s8, s19
	s_cselect_b32 s8, s28, s8
	s_sub_i32 s28, s8, s19
	s_cmp_ge_u32 s8, s19
	s_cselect_b32 s8, s28, s8
	s_xor_b32 s8, s8, s9
	s_sub_i32 s8, s8, s9
	s_add_i32 s8, s8, s18
	v_lshl_add_u32 v2, s8, 8, v208
	v_ashrrev_i32_e32 v3, 31, v2
	v_lshl_add_u64 v[2:3], v[2:3], 4, s[6:7]
	global_load_dwordx4 v[68:71], v[2:3], off
	v_readlane_b32 s29, v250, 29

.LBB0_334:
	s_ashr_i32 s8, s8, 3
	s_add_i32 s8, s9, s8
	s_ashr_i32 s9, s8, 31
	s_lshr_b32 s9, s9, 24
	s_add_i32 s9, s8, s9
	s_ashr_i32 s18, s9, 8
	s_lshl_b32 s18, s18, 3
	s_sub_i32 s19, 64, s18
	s_min_i32 s19, s19, 8
	s_abs_i32 s19, s19
	v_cvt_f32_u32_e32 v0, s19
	s_sub_i32 s28, 0, s19
	s_and_b32 s9, s9, 0xffffff00
	s_sub_i32 s8, s8, s9
	v_rcp_iflag_f32_e32 v0, v0
	s_ashr_i32 s9, s8, 31
	s_abs_i32 s8, s8
	v_mul_f32_e32 v0, 0x4f7ffffe, v0
	v_cvt_u32_f32_e32 v0, v0
	s_nop 0
	v_readfirstlane_b32 s29, v0
	s_mul_i32 s28, s28, s29
	s_mul_hi_u32 s28, s29, s28
	s_add_i32 s29, s29, s28
	s_mul_hi_u32 s28, s8, s29
	s_mul_i32 s28, s28, s19
	s_sub_i32 s8, s8, s28
	s_sub_i32 s28, s8, s19
	s_cmp_ge_u32 s8, s19
	s_cselect_b32 s8, s28, s8
	s_sub_i32 s28, s8, s19
	s_cmp_ge_u32 s8, s19
	s_cselect_b32 s8, s28, s8
	s_xor_b32 s8, s8, s9
	s_sub_i32 s8, s8, s9
	s_add_i32 s8, s8, s18
	v_lshl_add_u32 v2, s8, 8, v208
	v_ashrrev_i32_e32 v3, 31, v2
	v_lshl_add_u64 v[2:3], v[2:3], 4, s[6:7]
	global_load_dwordx4 v[72:75], v[2:3], off
	v_readlane_b32 s29, v250, 29

.LBB0_339:
	s_ashr_i32 s8, s8, 3
	s_add_i32 s8, s9, s8
	s_ashr_i32 s9, s8, 31
	s_lshr_b32 s9, s9, 24
	s_add_i32 s9, s8, s9
	s_ashr_i32 s18, s9, 8
	s_lshl_b32 s18, s18, 3
	s_sub_i32 s19, 64, s18
	s_min_i32 s19, s19, 8
	s_abs_i32 s19, s19
	v_cvt_f32_u32_e32 v0, s19
	s_sub_i32 s28, 0, s19
	s_and_b32 s9, s9, 0xffffff00
	s_sub_i32 s8, s8, s9
	v_rcp_iflag_f32_e32 v0, v0
	s_ashr_i32 s9, s8, 31
	s_abs_i32 s8, s8
	v_mul_f32_e32 v0, 0x4f7ffffe, v0
	v_cvt_u32_f32_e32 v0, v0
	s_nop 0
	v_readfirstlane_b32 s29, v0
	s_mul_i32 s28, s28, s29
	s_mul_hi_u32 s28, s29, s28
	s_add_i32 s29, s29, s28
	s_mul_hi_u32 s28, s8, s29
	s_mul_i32 s28, s28, s19
	s_sub_i32 s8, s8, s28
	s_sub_i32 s28, s8, s19
	s_cmp_ge_u32 s8, s19
	s_cselect_b32 s8, s28, s8
	s_sub_i32 s28, s8, s19
	s_cmp_ge_u32 s8, s19
	s_cselect_b32 s8, s28, s8
	s_xor_b32 s8, s8, s9
	s_sub_i32 s8, s8, s9
	s_add_i32 s8, s8, s18
	v_lshl_add_u32 v2, s8, 8, v208
	v_ashrrev_i32_e32 v3, 31, v2
	v_lshl_add_u64 v[2:3], v[2:3], 4, s[6:7]
	global_load_dwordx4 v[76:79], v[2:3], off
	v_readlane_b32 s29, v250, 29

.LBB0_344:
	s_ashr_i32 s8, s8, 3
	s_add_i32 s8, s9, s8
	s_ashr_i32 s9, s8, 31
	s_lshr_b32 s9, s9, 24
	s_add_i32 s9, s8, s9
	s_ashr_i32 s18, s9, 8
	s_lshl_b32 s18, s18, 3
	s_sub_i32 s19, 64, s18
	s_min_i32 s19, s19, 8
	s_abs_i32 s19, s19
	v_cvt_f32_u32_e32 v0, s19
	s_sub_i32 s28, 0, s19
	s_and_b32 s9, s9, 0xffffff00
	s_sub_i32 s8, s8, s9
	v_rcp_iflag_f32_e32 v0, v0
	s_ashr_i32 s9, s8, 31
	s_abs_i32 s8, s8
	v_mul_f32_e32 v0, 0x4f7ffffe, v0
	v_cvt_u32_f32_e32 v0, v0
	s_nop 0
	v_readfirstlane_b32 s29, v0
	s_mul_i32 s28, s28, s29
	s_mul_hi_u32 s28, s29, s28
	s_add_i32 s29, s29, s28
	s_mul_hi_u32 s28, s8, s29
	s_mul_i32 s28, s28, s19
	s_sub_i32 s8, s8, s28
	s_sub_i32 s28, s8, s19
	s_cmp_ge_u32 s8, s19
	s_cselect_b32 s8, s28, s8
	s_sub_i32 s28, s8, s19
	s_cmp_ge_u32 s8, s19
	s_cselect_b32 s8, s28, s8
	s_xor_b32 s8, s8, s9
	s_sub_i32 s8, s8, s9
	s_add_i32 s8, s8, s18
	v_lshl_add_u32 v2, s8, 8, v208
	v_ashrrev_i32_e32 v3, 31, v2
	v_lshl_add_u64 v[2:3], v[2:3], 4, s[6:7]
	global_load_dwordx4 v[80:83], v[2:3], off
	v_readlane_b32 s29, v250, 29

.LBB0_349:
	s_ashr_i32 s8, s8, 3
	s_add_i32 s8, s9, s8
	s_ashr_i32 s9, s8, 31
	s_lshr_b32 s9, s9, 24
	s_add_i32 s9, s8, s9
	s_ashr_i32 s18, s9, 8
	s_lshl_b32 s18, s18, 3
	s_sub_i32 s19, 64, s18
	s_min_i32 s19, s19, 8
	s_abs_i32 s19, s19
	v_cvt_f32_u32_e32 v0, s19
	s_sub_i32 s28, 0, s19
	s_and_b32 s9, s9, 0xffffff00
	s_sub_i32 s8, s8, s9
	v_rcp_iflag_f32_e32 v0, v0
	s_ashr_i32 s9, s8, 31
	s_abs_i32 s8, s8
	v_mul_f32_e32 v0, 0x4f7ffffe, v0
	v_cvt_u32_f32_e32 v0, v0
	s_nop 0
	v_readfirstlane_b32 s29, v0
	s_mul_i32 s28, s28, s29
	s_mul_hi_u32 s28, s29, s28
	s_add_i32 s29, s29, s28
	s_mul_hi_u32 s28, s8, s29
	s_mul_i32 s28, s28, s19
	s_sub_i32 s8, s8, s28
	s_sub_i32 s28, s8, s19
	s_cmp_ge_u32 s8, s19
	s_cselect_b32 s8, s28, s8
	s_sub_i32 s28, s8, s19
	s_cmp_ge_u32 s8, s19
	s_cselect_b32 s8, s28, s8
	s_xor_b32 s8, s8, s9
	s_sub_i32 s8, s8, s9
	s_add_i32 s8, s8, s18
	v_lshl_add_u32 v2, s8, 8, v208
	v_ashrrev_i32_e32 v3, 31, v2
	v_lshl_add_u64 v[2:3], v[2:3], 4, s[6:7]
	global_load_dwordx4 v[84:87], v[2:3], off
	v_readlane_b32 s29, v250, 29

.LBB0_354:
	s_ashr_i32 s8, s8, 3
	s_add_i32 s8, s9, s8
	s_ashr_i32 s9, s8, 31
	s_lshr_b32 s9, s9, 24
	s_add_i32 s9, s8, s9
	s_ashr_i32 s18, s9, 8
	s_lshl_b32 s18, s18, 3
	s_sub_i32 s19, 64, s18
	s_min_i32 s19, s19, 8
	s_abs_i32 s19, s19
	v_cvt_f32_u32_e32 v0, s19
	s_sub_i32 s24, 0, s19
	s_and_b32 s9, s9, 0xffffff00
	s_sub_i32 s8, s8, s9
	v_rcp_iflag_f32_e32 v0, v0
	s_ashr_i32 s9, s8, 31
	s_abs_i32 s8, s8
	v_mul_f32_e32 v0, 0x4f7ffffe, v0
	v_cvt_u32_f32_e32 v0, v0
	s_nop 0
	v_readfirstlane_b32 s25, v0
	s_mul_i32 s24, s24, s25
	s_mul_hi_u32 s24, s25, s24
	s_add_i32 s25, s25, s24
	s_mul_hi_u32 s24, s8, s25
	s_mul_i32 s24, s24, s19
	s_sub_i32 s8, s8, s24
	s_sub_i32 s24, s8, s19
	s_cmp_ge_u32 s8, s19
	s_cselect_b32 s8, s24, s8
	s_sub_i32 s24, s8, s19
	s_cmp_ge_u32 s8, s19
	s_cselect_b32 s8, s24, s8
	s_xor_b32 s8, s8, s9
	s_sub_i32 s8, s8, s9
	s_add_i32 s8, s8, s18
	v_lshl_add_u32 v2, s8, 8, v208
	v_ashrrev_i32_e32 v3, 31, v2
	v_lshl_add_u64 v[2:3], v[2:3], 4, s[6:7]
	global_load_dwordx4 v[88:91], v[2:3], off

.Lrt_tail_win:
	s_waitcnt vmcnt(0)
	v_cmp_gt_i32_e32 vcc, 0x100, v208
	s_and_saveexec_b64 s[98:99], vcc
	v_add_f32_e32 v92, v45, v44
	v_add_f32_e32 v93, v46, v47
	v_add_f32_e32 v92, v92, v93
	v_fmamk_f32 v92, v92, 0x3a800000, v196
	v_mul_f32_e32 v93, 0x4b800000, v92
	v_cmp_gt_f32_e32 vcc, s84, v92
	s_nop 1
	v_cndmask_b32_e32 v92, v92, v93, vcc
	v_rsq_f32_e32 v92, v92
	s_nop 0
	v_mul_f32_e32 v93, 0x45800000, v92
	v_cndmask_b32_e32 v92, v92, v93, vcc
	ds_write_b32 v141, v92
	v_add_f32_e32 v92, v49, v48
	v_add_f32_e32 v93, v50, v51
	v_add_f32_e32 v92, v92, v93
	v_fmamk_f32 v92, v92, 0x3a800000, v196
	v_mul_f32_e32 v93, 0x4b800000, v92
	v_cmp_gt_f32_e32 vcc, s84, v92
	s_nop 1
	v_cndmask_b32_e32 v92, v92, v93, vcc
	v_rsq_f32_e32 v92, v92
	s_nop 0
	v_mul_f32_e32 v93, 0x45800000, v92
	v_cndmask_b32_e32 v92, v92, v93, vcc
	ds_write_b32 v141, v92 offset:1024
	v_add_f32_e32 v92, v53, v52
	v_add_f32_e32 v93, v54, v55
	v_add_f32_e32 v92, v92, v93
	v_fmamk_f32 v92, v92, 0x3a800000, v196
	v_mul_f32_e32 v93, 0x4b800000, v92
	v_cmp_gt_f32_e32 vcc, s84, v92
	s_nop 1
	v_cndmask_b32_e32 v92, v92, v93, vcc
	v_rsq_f32_e32 v92, v92
	s_nop 0
	v_mul_f32_e32 v93, 0x45800000, v92
	v_cndmask_b32_e32 v92, v92, v93, vcc
	ds_write_b32 v141, v92 offset:2048
	v_add_f32_e32 v92, v57, v56
	v_add_f32_e32 v93, v58, v59
	v_add_f32_e32 v92, v92, v93
	v_fmamk_f32 v92, v92, 0x3a800000, v196
	v_mul_f32_e32 v93, 0x4b800000, v92
	v_cmp_gt_f32_e32 vcc, s84, v92
	s_nop 1
	v_cndmask_b32_e32 v92, v92, v93, vcc
	v_rsq_f32_e32 v92, v92
	s_nop 0
	v_mul_f32_e32 v93, 0x45800000, v92
	v_cndmask_b32_e32 v92, v92, v93, vcc
	ds_write_b32 v141, v92 offset:3072
	v_add_f32_e32 v92, v61, v60
	v_add_f32_e32 v93, v62, v63
	v_add_f32_e32 v92, v92, v93
	v_fmamk_f32 v92, v92, 0x3a800000, v196
	v_mul_f32_e32 v93, 0x4b800000, v92
	v_cmp_gt_f32_e32 vcc, s84, v92
	s_nop 1
	v_cndmask_b32_e32 v92, v92, v93, vcc
	v_rsq_f32_e32 v92, v92
	s_nop 0
	v_mul_f32_e32 v93, 0x45800000, v92
	v_cndmask_b32_e32 v92, v92, v93, vcc
	ds_write_b32 v141, v92 offset:4096
	v_add_f32_e32 v92, v65, v64
	v_add_f32_e32 v93, v66, v67
	v_add_f32_e32 v92, v92, v93
	v_fmamk_f32 v92, v92, 0x3a800000, v196
	v_mul_f32_e32 v93, 0x4b800000, v92
	v_cmp_gt_f32_e32 vcc, s84, v92
	s_nop 1
	v_cndmask_b32_e32 v92, v92, v93, vcc
	v_rsq_f32_e32 v92, v92
	s_nop 0
	v_mul_f32_e32 v93, 0x45800000, v92
	v_cndmask_b32_e32 v92, v92, v93, vcc
	ds_write_b32 v141, v92 offset:5120
	v_add_f32_e32 v92, v69, v68
	v_add_f32_e32 v93, v70, v71
	v_add_f32_e32 v92, v92, v93
	v_fmamk_f32 v92, v92, 0x3a800000, v196
	v_mul_f32_e32 v93, 0x4b800000, v92
	v_cmp_gt_f32_e32 vcc, s84, v92
	s_nop 1
	v_cndmask_b32_e32 v92, v92, v93, vcc
	v_rsq_f32_e32 v92, v92
	s_nop 0
	v_mul_f32_e32 v93, 0x45800000, v92
	v_cndmask_b32_e32 v92, v92, v93, vcc
	ds_write_b32 v141, v92 offset:6144
	v_add_f32_e32 v92, v73, v72
	v_add_f32_e32 v93, v74, v75
	v_add_f32_e32 v92, v92, v93
	v_fmamk_f32 v92, v92, 0x3a800000, v196
	v_mul_f32_e32 v93, 0x4b800000, v92
	v_cmp_gt_f32_e32 vcc, s84, v92
	s_nop 1
	v_cndmask_b32_e32 v92, v92, v93, vcc
	v_rsq_f32_e32 v92, v92
	s_nop 0
	v_mul_f32_e32 v93, 0x45800000, v92
	v_cndmask_b32_e32 v92, v92, v93, vcc
	ds_write_b32 v141, v92 offset:7168
	v_add_f32_e32 v92, v77, v76
	v_add_f32_e32 v93, v78, v79
	v_add_f32_e32 v92, v92, v93
	v_fmamk_f32 v92, v92, 0x3a800000, v196
	v_mul_f32_e32 v93, 0x4b800000, v92
	v_cmp_gt_f32_e32 vcc, s84, v92
	s_nop 1
	v_cndmask_b32_e32 v92, v92, v93, vcc
	v_rsq_f32_e32 v92, v92
	s_nop 0
	v_mul_f32_e32 v93, 0x45800000, v92
	v_cndmask_b32_e32 v92, v92, v93, vcc
	ds_write_b32 v141, v92 offset:8192
	v_add_f32_e32 v92, v81, v80
	v_add_f32_e32 v93, v82, v83
	v_add_f32_e32 v92, v92, v93
	v_fmamk_f32 v92, v92, 0x3a800000, v196
	v_mul_f32_e32 v93, 0x4b800000, v92
	v_cmp_gt_f32_e32 vcc, s84, v92
	s_nop 1
	v_cndmask_b32_e32 v92, v92, v93, vcc
	v_rsq_f32_e32 v92, v92
	s_nop 0
	v_mul_f32_e32 v93, 0x45800000, v92
	v_cndmask_b32_e32 v92, v92, v93, vcc
	ds_write_b32 v141, v92 offset:9216
	v_add_f32_e32 v92, v85, v84
	v_add_f32_e32 v93, v86, v87
	v_add_f32_e32 v92, v92, v93
	v_fmamk_f32 v92, v92, 0x3a800000, v196
	v_mul_f32_e32 v93, 0x4b800000, v92
	v_cmp_gt_f32_e32 vcc, s84, v92
	s_nop 1
	v_cndmask_b32_e32 v92, v92, v93, vcc
	v_rsq_f32_e32 v92, v92
	s_nop 0
	v_mul_f32_e32 v93, 0x45800000, v92
	v_cndmask_b32_e32 v92, v92, v93, vcc
	ds_write_b32 v141, v92 offset:10240
	v_add_f32_e32 v92, v89, v88
	v_add_f32_e32 v93, v90, v91
	v_add_f32_e32 v92, v92, v93
	v_fmamk_f32 v92, v92, 0x3a800000, v196
	v_mul_f32_e32 v93, 0x4b800000, v92
	v_cmp_gt_f32_e32 vcc, s84, v92
	s_nop 1
	v_cndmask_b32_e32 v92, v92, v93, vcc
	v_rsq_f32_e32 v92, v92
	s_nop 0
	v_mul_f32_e32 v93, 0x45800000, v92
	v_cndmask_b32_e32 v92, v92, v93, vcc
	ds_write_b32 v141, v92 offset:11264
	s_or_b64 exec, exec, s[98:99]

.LBB0_560:
	s_and_b64 vcc, exec, s[24:25]
	s_movk_i32 s3, 0x161
	s_cbranch_vccz .LBB0_613
	s_cmp_eq_u32 s29, 1
	s_cselect_b64 s[6:7], -1, 0
	s_ashr_i32 s13, s14, 31
	s_ashr_i32 s15, s12, 31
	s_cmpk_lt_i32 s12, 0xb00
	s_cselect_b64 s[20:21], -1, 0
	s_cmpk_gt_i32 s12, 0xaff
	s_cbranch_scc1 .LBB0_597
	s_and_b64 s[0:1], s[6:7], exec
	v_readlane_b32 s0, v250, 21
	v_readlane_b32 s4, v250, 25
	v_readlane_b32 s1, v250, 22
	v_readlane_b32 s5, v250, 26
	s_cselect_b32 s23, s1, s5
	s_cselect_b32 s22, s0, s4
	s_add_i32 s0, 0, 0x20000
	v_lshl_add_u32 v0, v208, 2, s0
	s_movk_i32 s0, 0xff
	s_movk_i32 s3, 0x100
	v_cmp_lt_i32_e64 s[0:1], s0, v208
	v_cmp_gt_i32_e64 s[4:5], s3, v208
	s_movk_i32 s3, 0x161
	s_and_saveexec_b64 s[24:25], s[4:5]
	s_cbranch_execz .LBB0_564
	s_lshr_b32 s8, s15, 29
	s_add_i32 s8, s12, s8
	s_and_b32 s9, s8, -8
	s_sub_i32 s9, s12, s9
	s_cmp_lt_i32 s9, 0
	s_cselect_b32 s18, s3, 0x160
	s_mul_i32 s9, s18, s9
	s_ashr_i32 s8, s8, 3
	s_add_i32 s9, s9, s8
	s_mul_hi_i32 s8, s9, 0x2e8ba2e9
	s_lshr_b32 s18, s8, 31
	s_ashr_i32 s8, s8, 5
	s_add_i32 s8, s8, s18
	s_mul_i32 s18, s8, 0xb0
	s_sub_i32 s9, s9, s18
	s_bfe_u32 s18, s9, 0x3001c
	s_add_i32 s18, s9, s18
	s_and_b32 s18, s18, 0xfff8
	s_sub_i32 s9, s9, s18
	s_sext_i32_i16 s9, s9
	s_lshl_b32 s8, s8, 11
	s_lshl_b32 s9, s9, 8
	s_add_i32 s9, s9, s8
	v_add_u32_e32 v2, s9, v208
	v_ashrrev_i32_e32 v3, 31, v2
	v_lshl_add_u64 v[2:3], v[2:3], 4, s[22:23]
	global_load_dwordx4 v[44:47], v[2:3], off
.LBB0_564:
	s_or_b64 exec, exec, s[24:25]
	s_add_u32 s24, s14, s12
	s_addc_u32 s25, s13, s15
	v_cmp_gt_i64_e32 vcc, s[24:25], v[176:177]
	s_cbranch_vccnz .Lrt_tail_up
	s_and_saveexec_b64 s[26:27], s[4:5]
	s_cbranch_execz .LBB0_567
	s_ashr_i32 s8, s24, 31
	s_lshr_b32 s8, s8, 29
	s_add_i32 s8, s24, s8
	s_ashr_i32 s9, s8, 3
	s_and_b32 s8, s8, -8
	s_sub_i32 s8, s24, s8
	s_cmp_lt_i32 s8, 0
	s_cselect_b32 s18, s3, 0x160
	s_mul_i32 s8, s18, s8
	s_add_i32 s8, s8, s9
	s_mul_hi_i32 s9, s8, 0x2e8ba2e9
	s_lshr_b32 s18, s9, 31
	s_ashr_i32 s9, s9, 5
	s_add_i32 s9, s9, s18
	s_lshl_b32 s18, s9, 3
	s_sub_i32 s19, 0x80, s18
	s_min_i32 s19, s19, 8
	s_abs_i32 s19, s19
	v_cvt_f32_u32_e32 v2, s19
	s_sub_i32 s28, 0, s19
	s_mulk_i32 s9, 0xb0
	s_sub_i32 s8, s8, s9
	v_rcp_iflag_f32_e32 v2, v2
	s_ashr_i32 s9, s8, 31
	s_abs_i32 s8, s8
	v_mul_f32_e32 v2, 0x4f7ffffe, v2
	v_cvt_u32_f32_e32 v2, v2
	s_nop 0
	v_readfirstlane_b32 s29, v2
	s_mul_i32 s28, s28, s29
	s_mul_hi_u32 s28, s29, s28
	s_add_i32 s29, s29, s28
	s_mul_hi_u32 s28, s8, s29
	s_mul_i32 s28, s28, s19
	s_sub_i32 s8, s8, s28
	s_sub_i32 s28, s8, s19
	s_cmp_ge_u32 s8, s19
	s_cselect_b32 s8, s28, s8
	s_sub_i32 s28, s8, s19
	s_cmp_ge_u32 s8, s19
	s_cselect_b32 s8, s28, s8
	s_xor_b32 s8, s8, s9
	s_sub_i32 s8, s8, s9
	s_add_i32 s8, s8, s18
	v_lshl_add_u32 v2, s8, 8, v208
	v_ashrrev_i32_e32 v3, 31, v2
	v_lshl_add_u64 v[2:3], v[2:3], 4, s[22:23]
	global_load_dwordx4 v[48:51], v[2:3], off
.LBB0_567:
	s_or_b64 exec, exec, s[26:27]
	s_add_u32 s24, s24, s14
	s_addc_u32 s25, s25, s13
	v_cmp_gt_i64_e32 vcc, s[24:25], v[176:177]
	s_cbranch_vccnz .Lrt_tail_up
	s_and_saveexec_b64 s[26:27], s[4:5]
	s_cbranch_execz .LBB0_570
	s_ashr_i32 s8, s24, 31
	s_lshr_b32 s8, s8, 29
	s_add_i32 s8, s24, s8
	s_ashr_i32 s9, s8, 3
	s_and_b32 s8, s8, -8
	s_sub_i32 s8, s24, s8
	s_cmp_lt_i32 s8, 0
	s_cselect_b32 s18, s3, 0x160
	s_mul_i32 s8, s18, s8
	s_add_i32 s8, s8, s9
	s_mul_hi_i32 s9, s8, 0x2e8ba2e9
	s_lshr_b32 s18, s9, 31
	s_ashr_i32 s9, s9, 5
	s_add_i32 s9, s9, s18
	s_lshl_b32 s18, s9, 3
	s_sub_i32 s19, 0x80, s18
	s_min_i32 s19, s19, 8
	s_abs_i32 s19, s19
	v_cvt_f32_u32_e32 v2, s19
	s_sub_i32 s28, 0, s19
	s_mulk_i32 s9, 0xb0
	s_sub_i32 s8, s8, s9
	v_rcp_iflag_f32_e32 v2, v2
	s_ashr_i32 s9, s8, 31
	s_abs_i32 s8, s8
	v_mul_f32_e32 v2, 0x4f7ffffe, v2
	v_cvt_u32_f32_e32 v2, v2
	s_nop 0
	v_readfirstlane_b32 s29, v2
	s_mul_i32 s28, s28, s29
	s_mul_hi_u32 s28, s29, s28
	s_add_i32 s29, s29, s28
	s_mul_hi_u32 s28, s8, s29
	s_mul_i32 s28, s28, s19
	s_sub_i32 s8, s8, s28
	s_sub_i32 s28, s8, s19
	s_cmp_ge_u32 s8, s19
	s_cselect_b32 s8, s28, s8
	s_sub_i32 s28, s8, s19
	s_cmp_ge_u32 s8, s19
	s_cselect_b32 s8, s28, s8
	s_xor_b32 s8, s8, s9
	s_sub_i32 s8, s8, s9
	s_add_i32 s8, s8, s18
	v_lshl_add_u32 v2, s8, 8, v208
	v_ashrrev_i32_e32 v3, 31, v2
	v_lshl_add_u64 v[2:3], v[2:3], 4, s[22:23]
	global_load_dwordx4 v[52:55], v[2:3], off
.LBB0_570:
	s_or_b64 exec, exec, s[26:27]
	s_add_u32 s24, s24, s14
	s_addc_u32 s25, s25, s13
	v_cmp_gt_i64_e32 vcc, s[24:25], v[176:177]
	s_cbranch_vccnz .Lrt_tail_up
	s_and_saveexec_b64 s[26:27], s[4:5]
	s_cbranch_execz .LBB0_573
	s_ashr_i32 s8, s24, 31
	s_lshr_b32 s8, s8, 29
	s_add_i32 s8, s24, s8
	s_ashr_i32 s9, s8, 3
	s_and_b32 s8, s8, -8
	s_sub_i32 s8, s24, s8
	s_cmp_lt_i32 s8, 0
	s_cselect_b32 s18, s3, 0x160
	s_mul_i32 s8, s18, s8
	s_add_i32 s8, s8, s9
	s_mul_hi_i32 s9, s8, 0x2e8ba2e9
	s_lshr_b32 s18, s9, 31
	s_ashr_i32 s9, s9, 5
	s_add_i32 s9, s9, s18
	s_lshl_b32 s18, s9, 3
	s_sub_i32 s19, 0x80, s18
	s_min_i32 s19, s19, 8
	s_abs_i32 s19, s19
	v_cvt_f32_u32_e32 v2, s19
	s_sub_i32 s28, 0, s19
	s_mulk_i32 s9, 0xb0
	s_sub_i32 s8, s8, s9
	v_rcp_iflag_f32_e32 v2, v2
	s_ashr_i32 s9, s8, 31
	s_abs_i32 s8, s8
	v_mul_f32_e32 v2, 0x4f7ffffe, v2
	v_cvt_u32_f32_e32 v2, v2
	s_nop 0
	v_readfirstlane_b32 s29, v2
	s_mul_i32 s28, s28, s29
	s_mul_hi_u32 s28, s29, s28
	s_add_i32 s29, s29, s28
	s_mul_hi_u32 s28, s8, s29
	s_mul_i32 s28, s28, s19
	s_sub_i32 s8, s8, s28
	s_sub_i32 s28, s8, s19
	s_cmp_ge_u32 s8, s19
	s_cselect_b32 s8, s28, s8
	s_sub_i32 s28, s8, s19
	s_cmp_ge_u32 s8, s19
	s_cselect_b32 s8, s28, s8
	s_xor_b32 s8, s8, s9
	s_sub_i32 s8, s8, s9
	s_add_i32 s8, s8, s18
	v_lshl_add_u32 v2, s8, 8, v208
	v_ashrrev_i32_e32 v3, 31, v2
	v_lshl_add_u64 v[2:3], v[2:3], 4, s[22:23]
	global_load_dwordx4 v[56:59], v[2:3], off
.LBB0_573:
	s_or_b64 exec, exec, s[26:27]
	s_add_u32 s24, s24, s14
	s_addc_u32 s25, s25, s13
	v_cmp_gt_i64_e32 vcc, s[24:25], v[176:177]
	s_cbranch_vccnz .Lrt_tail_up
	s_and_saveexec_b64 s[26:27], s[4:5]
	s_cbranch_execz .LBB0_576
	s_ashr_i32 s8, s24, 31
	s_lshr_b32 s8, s8, 29
	s_add_i32 s8, s24, s8
	s_ashr_i32 s9, s8, 3
	s_and_b32 s8, s8, -8
	s_sub_i32 s8, s24, s8
	s_cmp_lt_i32 s8, 0
	s_cselect_b32 s18, s3, 0x160
	s_mul_i32 s8, s18, s8
	s_add_i32 s8, s8, s9
	s_mul_hi_i32 s9, s8, 0x2e8ba2e9
	s_lshr_b32 s18, s9, 31
	s_ashr_i32 s9, s9, 5
	s_add_i32 s9, s9, s18
	s_lshl_b32 s18, s9, 3
	s_sub_i32 s19, 0x80, s18
	s_min_i32 s19, s19, 8
	s_abs_i32 s19, s19
	v_cvt_f32_u32_e32 v2, s19
	s_sub_i32 s28, 0, s19
	s_mulk_i32 s9, 0xb0
	s_sub_i32 s8, s8, s9
	v_rcp_iflag_f32_e32 v2, v2
	s_ashr_i32 s9, s8, 31
	s_abs_i32 s8, s8
	v_mul_f32_e32 v2, 0x4f7ffffe, v2
	v_cvt_u32_f32_e32 v2, v2
	s_nop 0
	v_readfirstlane_b32 s29, v2
	s_mul_i32 s28, s28, s29
	s_mul_hi_u32 s28, s29, s28
	s_add_i32 s29, s29, s28
	s_mul_hi_u32 s28, s8, s29
	s_mul_i32 s28, s28, s19
	s_sub_i32 s8, s8, s28
	s_sub_i32 s28, s8, s19
	s_cmp_ge_u32 s8, s19
	s_cselect_b32 s8, s28, s8
	s_sub_i32 s28, s8, s19
	s_cmp_ge_u32 s8, s19
	s_cselect_b32 s8, s28, s8
	s_xor_b32 s8, s8, s9
	s_sub_i32 s8, s8, s9
	s_add_i32 s8, s8, s18
	v_lshl_add_u32 v2, s8, 8, v208
	v_ashrrev_i32_e32 v3, 31, v2
	v_lshl_add_u64 v[2:3], v[2:3], 4, s[22:23]
	global_load_dwordx4 v[60:63], v[2:3], off
.LBB0_576:
	s_or_b64 exec, exec, s[26:27]
	s_add_u32 s24, s24, s14
	s_addc_u32 s25, s25, s13
	v_cmp_gt_i64_e32 vcc, s[24:25], v[176:177]
	s_cbranch_vccnz .Lrt_tail_up
	s_and_saveexec_b64 s[26:27], s[4:5]
	s_cbranch_execz .LBB0_579
	s_ashr_i32 s8, s24, 31
	s_lshr_b32 s8, s8, 29
	s_add_i32 s8, s24, s8
	s_ashr_i32 s9, s8, 3
	s_and_b32 s8, s8, -8
	s_sub_i32 s8, s24, s8
	s_cmp_lt_i32 s8, 0
	s_cselect_b32 s18, s3, 0x160
	s_mul_i32 s8, s18, s8
	s_add_i32 s8, s8, s9
	s_mul_hi_i32 s9, s8, 0x2e8ba2e9
	s_lshr_b32 s18, s9, 31
	s_ashr_i32 s9, s9, 5
	s_add_i32 s9, s9, s18
	s_lshl_b32 s18, s9, 3
	s_sub_i32 s19, 0x80, s18
	s_min_i32 s19, s19, 8
	s_abs_i32 s19, s19
	v_cvt_f32_u32_e32 v2, s19
	s_sub_i32 s28, 0, s19
	s_mulk_i32 s9, 0xb0
	s_sub_i32 s8, s8, s9
	v_rcp_iflag_f32_e32 v2, v2
	s_ashr_i32 s9, s8, 31
	s_abs_i32 s8, s8
	v_mul_f32_e32 v2, 0x4f7ffffe, v2
	v_cvt_u32_f32_e32 v2, v2
	s_nop 0
	v_readfirstlane_b32 s29, v2
	s_mul_i32 s28, s28, s29
	s_mul_hi_u32 s28, s29, s28
	s_add_i32 s29, s29, s28
	s_mul_hi_u32 s28, s8, s29
	s_mul_i32 s28, s28, s19
	s_sub_i32 s8, s8, s28
	s_sub_i32 s28, s8, s19
	s_cmp_ge_u32 s8, s19
	s_cselect_b32 s8, s28, s8
	s_sub_i32 s28, s8, s19
	s_cmp_ge_u32 s8, s19
	s_cselect_b32 s8, s28, s8
	s_xor_b32 s8, s8, s9
	s_sub_i32 s8, s8, s9
	s_add_i32 s8, s8, s18
	v_lshl_add_u32 v2, s8, 8, v208
	v_ashrrev_i32_e32 v3, 31, v2
	v_lshl_add_u64 v[2:3], v[2:3], 4, s[22:23]
	global_load_dwordx4 v[64:67], v[2:3], off
.LBB0_579:
	s_or_b64 exec, exec, s[26:27]
	s_add_u32 s24, s24, s14
	s_addc_u32 s25, s25, s13
	v_cmp_gt_i64_e32 vcc, s[24:25], v[176:177]
	s_cbranch_vccnz .Lrt_tail_up
	s_and_saveexec_b64 s[26:27], s[4:5]
	s_cbranch_execz .LBB0_582
	s_ashr_i32 s8, s24, 31
	s_lshr_b32 s8, s8, 29
	s_add_i32 s8, s24, s8
	s_ashr_i32 s9, s8, 3
	s_and_b32 s8, s8, -8
	s_sub_i32 s8, s24, s8
	s_cmp_lt_i32 s8, 0
	s_cselect_b32 s18, s3, 0x160
	s_mul_i32 s8, s18, s8
	s_add_i32 s8, s8, s9
	s_mul_hi_i32 s9, s8, 0x2e8ba2e9
	s_lshr_b32 s18, s9, 31
	s_ashr_i32 s9, s9, 5
	s_add_i32 s9, s9, s18
	s_lshl_b32 s18, s9, 3
	s_sub_i32 s19, 0x80, s18
	s_min_i32 s19, s19, 8
	s_abs_i32 s19, s19
	v_cvt_f32_u32_e32 v2, s19
	s_sub_i32 s28, 0, s19
	s_mulk_i32 s9, 0xb0
	s_sub_i32 s8, s8, s9
	v_rcp_iflag_f32_e32 v2, v2
	s_ashr_i32 s9, s8, 31
	s_abs_i32 s8, s8
	v_mul_f32_e32 v2, 0x4f7ffffe, v2
	v_cvt_u32_f32_e32 v2, v2
	s_nop 0
	v_readfirstlane_b32 s29, v2
	s_mul_i32 s28, s28, s29
	s_mul_hi_u32 s28, s29, s28
	s_add_i32 s29, s29, s28
	s_mul_hi_u32 s28, s8, s29
	s_mul_i32 s28, s28, s19
	s_sub_i32 s8, s8, s28
	s_sub_i32 s28, s8, s19
	s_cmp_ge_u32 s8, s19
	s_cselect_b32 s8, s28, s8
	s_sub_i32 s28, s8, s19
	s_cmp_ge_u32 s8, s19
	s_cselect_b32 s8, s28, s8
	s_xor_b32 s8, s8, s9
	s_sub_i32 s8, s8, s9
	s_add_i32 s8, s8, s18
	v_lshl_add_u32 v2, s8, 8, v208
	v_ashrrev_i32_e32 v3, 31, v2
	v_lshl_add_u64 v[2:3], v[2:3], 4, s[22:23]
	global_load_dwordx4 v[68:71], v[2:3], off
.LBB0_582:
	s_or_b64 exec, exec, s[26:27]
	s_add_u32 s24, s24, s14
	s_addc_u32 s25, s25, s13
	v_cmp_gt_i64_e32 vcc, s[24:25], v[176:177]
	s_cbranch_vccnz .Lrt_tail_up
	s_and_saveexec_b64 s[26:27], s[4:5]
	s_cbranch_execz .LBB0_585
	s_ashr_i32 s8, s24, 31
	s_lshr_b32 s8, s8, 29
	s_add_i32 s8, s24, s8
	s_ashr_i32 s9, s8, 3
	s_and_b32 s8, s8, -8
	s_sub_i32 s8, s24, s8
	s_cmp_lt_i32 s8, 0
	s_cselect_b32 s18, s3, 0x160
	s_mul_i32 s8, s18, s8
	s_add_i32 s8, s8, s9
	s_mul_hi_i32 s9, s8, 0x2e8ba2e9
	s_lshr_b32 s18, s9, 31
	s_ashr_i32 s9, s9, 5
	s_add_i32 s9, s9, s18
	s_lshl_b32 s18, s9, 3
	s_sub_i32 s19, 0x80, s18
	s_min_i32 s19, s19, 8
	s_abs_i32 s19, s19
	v_cvt_f32_u32_e32 v2, s19
	s_sub_i32 s28, 0, s19
	s_mulk_i32 s9, 0xb0
	s_sub_i32 s8, s8, s9
	v_rcp_iflag_f32_e32 v2, v2
	s_ashr_i32 s9, s8, 31
	s_abs_i32 s8, s8
	v_mul_f32_e32 v2, 0x4f7ffffe, v2
	v_cvt_u32_f32_e32 v2, v2
	s_nop 0
	v_readfirstlane_b32 s29, v2
	s_mul_i32 s28, s28, s29
	s_mul_hi_u32 s28, s29, s28
	s_add_i32 s29, s29, s28
	s_mul_hi_u32 s28, s8, s29
	s_mul_i32 s28, s28, s19
	s_sub_i32 s8, s8, s28
	s_sub_i32 s28, s8, s19
	s_cmp_ge_u32 s8, s19
	s_cselect_b32 s8, s28, s8
	s_sub_i32 s28, s8, s19
	s_cmp_ge_u32 s8, s19
	s_cselect_b32 s8, s28, s8
	s_xor_b32 s8, s8, s9
	s_sub_i32 s8, s8, s9
	s_add_i32 s8, s8, s18
	v_lshl_add_u32 v2, s8, 8, v208
	v_ashrrev_i32_e32 v3, 31, v2
	v_lshl_add_u64 v[2:3], v[2:3], 4, s[22:23]
	global_load_dwordx4 v[72:75], v[2:3], off
.LBB0_585:
	s_or_b64 exec, exec, s[26:27]
	s_add_u32 s24, s24, s14
	s_addc_u32 s25, s25, s13
	v_cmp_gt_i64_e32 vcc, s[24:25], v[176:177]
	s_cbranch_vccnz .Lrt_tail_up
	s_and_saveexec_b64 s[26:27], s[4:5]
	s_cbranch_execz .LBB0_588
	s_ashr_i32 s8, s24, 31
	s_lshr_b32 s8, s8, 29
	s_add_i32 s8, s24, s8
	s_ashr_i32 s9, s8, 3
	s_and_b32 s8, s8, -8
	s_sub_i32 s8, s24, s8
	s_cmp_lt_i32 s8, 0
	s_cselect_b32 s18, s3, 0x160
	s_mul_i32 s8, s18, s8
	s_add_i32 s8, s8, s9
	s_mul_hi_i32 s9, s8, 0x2e8ba2e9
	s_lshr_b32 s18, s9, 31
	s_ashr_i32 s9, s9, 5
	s_add_i32 s9, s9, s18
	s_lshl_b32 s18, s9, 3
	s_sub_i32 s19, 0x80, s18
	s_min_i32 s19, s19, 8
	s_abs_i32 s19, s19
	v_cvt_f32_u32_e32 v2, s19
	s_sub_i32 s28, 0, s19
	s_mulk_i32 s9, 0xb0
	s_sub_i32 s8, s8, s9
	v_rcp_iflag_f32_e32 v2, v2
	s_ashr_i32 s9, s8, 31
	s_abs_i32 s8, s8
	v_mul_f32_e32 v2, 0x4f7ffffe, v2
	v_cvt_u32_f32_e32 v2, v2
	s_nop 0
	v_readfirstlane_b32 s29, v2
	s_mul_i32 s28, s28, s29
	s_mul_hi_u32 s28, s29, s28
	s_add_i32 s29, s29, s28
	s_mul_hi_u32 s28, s8, s29
	s_mul_i32 s28, s28, s19
	s_sub_i32 s8, s8, s28
	s_sub_i32 s28, s8, s19
	s_cmp_ge_u32 s8, s19
	s_cselect_b32 s8, s28, s8
	s_sub_i32 s28, s8, s19
	s_cmp_ge_u32 s8, s19
	s_cselect_b32 s8, s28, s8
	s_xor_b32 s8, s8, s9
	s_sub_i32 s8, s8, s9
	s_add_i32 s8, s8, s18
	v_lshl_add_u32 v2, s8, 8, v208
	v_ashrrev_i32_e32 v3, 31, v2
	v_lshl_add_u64 v[2:3], v[2:3], 4, s[22:23]
	global_load_dwordx4 v[76:79], v[2:3], off
.LBB0_588:
	s_or_b64 exec, exec, s[26:27]
	s_add_u32 s24, s24, s14
	s_addc_u32 s25, s25, s13
	v_cmp_gt_i64_e32 vcc, s[24:25], v[176:177]
	s_cbranch_vccnz .Lrt_tail_up
	s_and_saveexec_b64 s[26:27], s[4:5]
	s_cbranch_execz .LBB0_591
	s_ashr_i32 s8, s24, 31
	s_lshr_b32 s8, s8, 29
	s_add_i32 s8, s24, s8
	s_ashr_i32 s9, s8, 3
	s_and_b32 s8, s8, -8
	s_sub_i32 s8, s24, s8
	s_cmp_lt_i32 s8, 0
	s_cselect_b32 s18, s3, 0x160
	s_mul_i32 s8, s18, s8
	s_add_i32 s8, s8, s9
	s_mul_hi_i32 s9, s8, 0x2e8ba2e9
	s_lshr_b32 s18, s9, 31
	s_ashr_i32 s9, s9, 5
	s_add_i32 s9, s9, s18
	s_lshl_b32 s18, s9, 3
	s_sub_i32 s19, 0x80, s18
	s_min_i32 s19, s19, 8
	s_abs_i32 s19, s19
	v_cvt_f32_u32_e32 v2, s19
	s_sub_i32 s28, 0, s19
	s_mulk_i32 s9, 0xb0
	s_sub_i32 s8, s8, s9
	v_rcp_iflag_f32_e32 v2, v2
	s_ashr_i32 s9, s8, 31
	s_abs_i32 s8, s8
	v_mul_f32_e32 v2, 0x4f7ffffe, v2
	v_cvt_u32_f32_e32 v2, v2
	s_nop 0
	v_readfirstlane_b32 s29, v2
	s_mul_i32 s28, s28, s29
	s_mul_hi_u32 s28, s29, s28
	s_add_i32 s29, s29, s28
	s_mul_hi_u32 s28, s8, s29
	s_mul_i32 s28, s28, s19
	s_sub_i32 s8, s8, s28
	s_sub_i32 s28, s8, s19
	s_cmp_ge_u32 s8, s19
	s_cselect_b32 s8, s28, s8
	s_sub_i32 s28, s8, s19
	s_cmp_ge_u32 s8, s19
	s_cselect_b32 s8, s28, s8
	s_xor_b32 s8, s8, s9
	s_sub_i32 s8, s8, s9
	s_add_i32 s8, s8, s18
	v_lshl_add_u32 v2, s8, 8, v208
	v_ashrrev_i32_e32 v3, 31, v2
	v_lshl_add_u64 v[2:3], v[2:3], 4, s[22:23]
	global_load_dwordx4 v[80:83], v[2:3], off
.LBB0_591:
	s_or_b64 exec, exec, s[26:27]
	s_add_u32 s24, s24, s14
	s_addc_u32 s25, s25, s13
	v_cmp_gt_i64_e32 vcc, s[24:25], v[176:177]
	s_cbranch_vccnz .Lrt_tail_up
	s_and_saveexec_b64 s[26:27], s[4:5]
	s_cbranch_execz .LBB0_594
	s_ashr_i32 s4, s24, 31
	s_lshr_b32 s4, s4, 29
	s_add_i32 s4, s24, s4
	s_ashr_i32 s5, s4, 3
	s_and_b32 s4, s4, -8
	s_sub_i32 s4, s24, s4
	s_cmp_lt_i32 s4, 0
	s_cselect_b32 s8, s3, 0x160
	s_mul_i32 s4, s8, s4
	s_add_i32 s4, s4, s5
	s_mul_hi_i32 s5, s4, 0x2e8ba2e9
	s_lshr_b32 s8, s5, 31
	s_ashr_i32 s5, s5, 5
	s_add_i32 s5, s5, s8
	s_lshl_b32 s8, s5, 3
	s_sub_i32 s9, 0x80, s8
	s_min_i32 s9, s9, 8
	s_abs_i32 s9, s9
	v_cvt_f32_u32_e32 v2, s9
	s_sub_i32 s18, 0, s9
	s_mulk_i32 s5, 0xb0
	s_sub_i32 s4, s4, s5
	v_rcp_iflag_f32_e32 v2, v2
	s_ashr_i32 s5, s4, 31
	s_abs_i32 s4, s4
	v_mul_f32_e32 v2, 0x4f7ffffe, v2
	v_cvt_u32_f32_e32 v2, v2
	s_nop 0
	v_readfirstlane_b32 s19, v2
	s_mul_i32 s18, s18, s19
	s_mul_hi_u32 s18, s19, s18
	s_add_i32 s19, s19, s18
	s_mul_hi_u32 s18, s4, s19
	s_mul_i32 s18, s18, s9
	s_sub_i32 s4, s4, s18
	s_sub_i32 s18, s4, s9
	s_cmp_ge_u32 s4, s9
	s_cselect_b32 s4, s18, s4
	s_sub_i32 s18, s4, s9
	s_cmp_ge_u32 s4, s9
	s_cselect_b32 s4, s18, s4
	s_xor_b32 s4, s4, s5
	s_sub_i32 s4, s4, s5
	s_add_i32 s4, s4, s8
	v_lshl_add_u32 v2, s4, 8, v208
	v_ashrrev_i32_e32 v3, 31, v2
	v_lshl_add_u64 v[2:3], v[2:3], 4, s[22:23]
	global_load_dwordx4 v[84:87], v[2:3], off
.LBB0_594:
	s_or_b64 exec, exec, s[26:27]
	s_add_u32 s4, s24, s14
	s_addc_u32 s5, s25, s13
	v_cmp_lt_i64_e32 vcc, s[4:5], v[178:179]
	s_xor_b64 s[0:1], s[0:1], -1
	s_and_b64 s[0:1], vcc, s[0:1]
	s_and_saveexec_b64 s[8:9], s[0:1]
	s_xor_b64 s[0:1], exec, s[8:9]
	s_cbranch_execz .LBB0_596
	s_ashr_i32 s5, s4, 31
	s_lshr_b32 s5, s5, 29
	s_add_i32 s5, s4, s5
	s_ashr_i32 s8, s5, 3
	s_and_b32 s5, s5, -8
	s_sub_i32 s4, s4, s5
	s_cmp_lt_i32 s4, 0
	s_cselect_b32 s5, s3, 0x160
	s_mul_i32 s4, s5, s4
	s_add_i32 s4, s4, s8
	s_mul_hi_i32 s5, s4, 0x2e8ba2e9
	s_lshr_b32 s8, s5, 31
	s_ashr_i32 s5, s5, 5
	s_add_i32 s5, s5, s8
	s_lshl_b32 s8, s5, 3
	s_sub_i32 s9, 0x80, s8
	s_min_i32 s9, s9, 8
	s_abs_i32 s9, s9
	v_cvt_f32_u32_e32 v2, s9
	s_sub_i32 s18, 0, s9
	s_mulk_i32 s5, 0xb0
	s_sub_i32 s4, s4, s5
	v_rcp_iflag_f32_e32 v2, v2
	s_ashr_i32 s5, s4, 31
	s_abs_i32 s4, s4
	v_mul_f32_e32 v2, 0x4f7ffffe, v2
	v_cvt_u32_f32_e32 v2, v2
	s_nop 0
	v_readfirstlane_b32 s19, v2
	s_mul_i32 s18, s18, s19
	s_mul_hi_u32 s18, s19, s18
	s_add_i32 s19, s19, s18
	s_mul_hi_u32 s18, s4, s19
	s_mul_i32 s18, s18, s9
	s_sub_i32 s4, s4, s18
	s_sub_i32 s18, s4, s9
	s_cmp_ge_u32 s4, s9
	s_cselect_b32 s4, s18, s4
	s_sub_i32 s18, s4, s9
	s_cmp_ge_u32 s4, s9
	s_cselect_b32 s4, s18, s4
	s_xor_b32 s4, s4, s5
	s_sub_i32 s4, s4, s5
	s_add_i32 s4, s4, s8
	v_lshl_add_u32 v2, s4, 8, v208
	v_ashrrev_i32_e32 v3, 31, v2
	v_lshl_add_u64 v[2:3], v[2:3], 4, s[22:23]
	global_load_dwordx4 v[88:91], v[2:3], off

.Lrt_tail_up:
	s_waitcnt vmcnt(0)
	v_cmp_gt_i32_e32 vcc, 0x100, v208
	s_and_saveexec_b64 s[98:99], vcc
	v_add_f32_e32 v92, v45, v44
	v_add_f32_e32 v93, v46, v47
	v_add_f32_e32 v92, v92, v93
	v_fmamk_f32 v92, v92, 0x3a800000, v196
	v_mul_f32_e32 v93, 0x4b800000, v92
	v_cmp_gt_f32_e32 vcc, s84, v92
	s_nop 1
	v_cndmask_b32_e32 v92, v92, v93, vcc
	v_rsq_f32_e32 v92, v92
	s_nop 0
	v_mul_f32_e32 v93, 0x45800000, v92
	v_cndmask_b32_e32 v92, v92, v93, vcc
	ds_write_b32 v0, v92
	v_add_f32_e32 v92, v49, v48
	v_add_f32_e32 v93, v50, v51
	v_add_f32_e32 v92, v92, v93
	v_fmamk_f32 v92, v92, 0x3a800000, v196
	v_mul_f32_e32 v93, 0x4b800000, v92
	v_cmp_gt_f32_e32 vcc, s84, v92
	s_nop 1
	v_cndmask_b32_e32 v92, v92, v93, vcc
	v_rsq_f32_e32 v92, v92
	s_nop 0
	v_mul_f32_e32 v93, 0x45800000, v92
	v_cndmask_b32_e32 v92, v92, v93, vcc
	ds_write_b32 v0, v92 offset:1024
	v_add_f32_e32 v92, v53, v52
	v_add_f32_e32 v93, v54, v55
	v_add_f32_e32 v92, v92, v93
	v_fmamk_f32 v92, v92, 0x3a800000, v196
	v_mul_f32_e32 v93, 0x4b800000, v92
	v_cmp_gt_f32_e32 vcc, s84, v92
	s_nop 1
	v_cndmask_b32_e32 v92, v92, v93, vcc
	v_rsq_f32_e32 v92, v92
	s_nop 0
	v_mul_f32_e32 v93, 0x45800000, v92
	v_cndmask_b32_e32 v92, v92, v93, vcc
	ds_write_b32 v0, v92 offset:2048
	v_add_f32_e32 v92, v57, v56
	v_add_f32_e32 v93, v58, v59
	v_add_f32_e32 v92, v92, v93
	v_fmamk_f32 v92, v92, 0x3a800000, v196
	v_mul_f32_e32 v93, 0x4b800000, v92
	v_cmp_gt_f32_e32 vcc, s84, v92
	s_nop 1
	v_cndmask_b32_e32 v92, v92, v93, vcc
	v_rsq_f32_e32 v92, v92
	s_nop 0
	v_mul_f32_e32 v93, 0x45800000, v92
	v_cndmask_b32_e32 v92, v92, v93, vcc
	ds_write_b32 v0, v92 offset:3072
	v_add_f32_e32 v92, v61, v60
	v_add_f32_e32 v93, v62, v63
	v_add_f32_e32 v92, v92, v93
	v_fmamk_f32 v92, v92, 0x3a800000, v196
	v_mul_f32_e32 v93, 0x4b800000, v92
	v_cmp_gt_f32_e32 vcc, s84, v92
	s_nop 1
	v_cndmask_b32_e32 v92, v92, v93, vcc
	v_rsq_f32_e32 v92, v92
	s_nop 0
	v_mul_f32_e32 v93, 0x45800000, v92
	v_cndmask_b32_e32 v92, v92, v93, vcc
	ds_write_b32 v0, v92 offset:4096
	v_add_f32_e32 v92, v65, v64
	v_add_f32_e32 v93, v66, v67
	v_add_f32_e32 v92, v92, v93
	v_fmamk_f32 v92, v92, 0x3a800000, v196
	v_mul_f32_e32 v93, 0x4b800000, v92
	v_cmp_gt_f32_e32 vcc, s84, v92
	s_nop 1
	v_cndmask_b32_e32 v92, v92, v93, vcc
	v_rsq_f32_e32 v92, v92
	s_nop 0
	v_mul_f32_e32 v93, 0x45800000, v92
	v_cndmask_b32_e32 v92, v92, v93, vcc
	ds_write_b32 v0, v92 offset:5120
	v_add_f32_e32 v92, v69, v68
	v_add_f32_e32 v93, v70, v71
	v_add_f32_e32 v92, v92, v93
	v_fmamk_f32 v92, v92, 0x3a800000, v196
	v_mul_f32_e32 v93, 0x4b800000, v92
	v_cmp_gt_f32_e32 vcc, s84, v92
	s_nop 1
	v_cndmask_b32_e32 v92, v92, v93, vcc
	v_rsq_f32_e32 v92, v92
	s_nop 0
	v_mul_f32_e32 v93, 0x45800000, v92
	v_cndmask_b32_e32 v92, v92, v93, vcc
	ds_write_b32 v0, v92 offset:6144
	v_add_f32_e32 v92, v73, v72
	v_add_f32_e32 v93, v74, v75
	v_add_f32_e32 v92, v92, v93
	v_fmamk_f32 v92, v92, 0x3a800000, v196
	v_mul_f32_e32 v93, 0x4b800000, v92
	v_cmp_gt_f32_e32 vcc, s84, v92
	s_nop 1
	v_cndmask_b32_e32 v92, v92, v93, vcc
	v_rsq_f32_e32 v92, v92
	s_nop 0
	v_mul_f32_e32 v93, 0x45800000, v92
	v_cndmask_b32_e32 v92, v92, v93, vcc
	ds_write_b32 v0, v92 offset:7168
	v_add_f32_e32 v92, v77, v76
	v_add_f32_e32 v93, v78, v79
	v_add_f32_e32 v92, v92, v93
	v_fmamk_f32 v92, v92, 0x3a800000, v196
	v_mul_f32_e32 v93, 0x4b800000, v92
	v_cmp_gt_f32_e32 vcc, s84, v92
	s_nop 1
	v_cndmask_b32_e32 v92, v92, v93, vcc
	v_rsq_f32_e32 v92, v92
	s_nop 0
	v_mul_f32_e32 v93, 0x45800000, v92
	v_cndmask_b32_e32 v92, v92, v93, vcc
	ds_write_b32 v0, v92 offset:8192
	v_add_f32_e32 v92, v81, v80
	v_add_f32_e32 v93, v82, v83
	v_add_f32_e32 v92, v92, v93
	v_fmamk_f32 v92, v92, 0x3a800000, v196
	v_mul_f32_e32 v93, 0x4b800000, v92
	v_cmp_gt_f32_e32 vcc, s84, v92
	s_nop 1
	v_cndmask_b32_e32 v92, v92, v93, vcc
	v_rsq_f32_e32 v92, v92
	s_nop 0
	v_mul_f32_e32 v93, 0x45800000, v92
	v_cndmask_b32_e32 v92, v92, v93, vcc
	ds_write_b32 v0, v92 offset:9216
	v_add_f32_e32 v92, v85, v84
	v_add_f32_e32 v93, v86, v87
	v_add_f32_e32 v92, v92, v93
	v_fmamk_f32 v92, v92, 0x3a800000, v196
	v_mul_f32_e32 v93, 0x4b800000, v92
	v_cmp_gt_f32_e32 vcc, s84, v92
	s_nop 1
	v_cndmask_b32_e32 v92, v92, v93, vcc
	v_rsq_f32_e32 v92, v92
	s_nop 0
	v_mul_f32_e32 v93, 0x45800000, v92
	v_cndmask_b32_e32 v92, v92, v93, vcc
	ds_write_b32 v0, v92 offset:10240
	v_add_f32_e32 v92, v89, v88
	v_add_f32_e32 v93, v90, v91
	v_add_f32_e32 v92, v92, v93
	v_fmamk_f32 v92, v92, 0x3a800000, v196
	v_mul_f32_e32 v93, 0x4b800000, v92
	v_cmp_gt_f32_e32 vcc, s84, v92
	s_nop 1
	v_cndmask_b32_e32 v92, v92, v93, vcc
	v_rsq_f32_e32 v92, v92
	s_nop 0
	v_mul_f32_e32 v93, 0x45800000, v92
	v_cndmask_b32_e32 v92, v92, v93, vcc
	ds_write_b32 v0, v92 offset:11264
	s_or_b64 exec, exec, s[98:99]
